# P1 V^T epilogue: lane-quad 8ch x 4tok transpose with DPP/v_perm/v_cndmask, two 8-byte stores per block instead of eight 2-byte stores (no LDS)
# baseline (speedup 1.0000x reference)
; DI unsigned pk2(float lo, float hi) { f32x2_t v = {lo, hi}; bf16x2_t b = __builtin_convertvector(v, bf16x2_t); return __builtin_bit_cast(unsigned, b); }
; DI int rot_t(int c, int t) { return (t + 128 * c) & (MTOK - 1); }
;     DI void operator()(AccRef acc, const Unit& u, int wr, int wc, int fr, int fq) const {
;     ...
;                 const int row = row0 + ai * HALF + m * 16;
;                 float rs = rsqrtf(SS0[row] * (1.0f / DM) + EPSN); if (pn < 2) rs *= 0.125f;
; #pragma unroll
;                 for (int bj = 0; bj < 2; ++bj) {
;                     const f32x4 v0 = acc[ai][bj][m][0] * rs, v1 = acc[ai][bj][m][1] * rs;
;                     u32x4 w; w.x = pk2(v0[0], v0[1]); w.y = pk2(v0[2], v0[3]); w.z = pk2(v1[0], v1[1]); w.w = pk2(v1[2], v1[3]);
;                     const int ct = bj * HALF + cb;
;                     if (pn < 2)      *(u32x4*)(Q + (size_t)row * 512 + pn * 256 + ct) = w;
;                     else if (pn < 4) *(u32x4*)(K + (size_t)row * 512 + (pn - 2) * 256 + ct) = w;
;                     else if (pn < 6) { const int vc = (pn - 4) * 256 + ct; const unsigned wv[4] = {w.x, w.y, w.z, w.w};
; _Pragma("unroll")
;                         for (int e = 0; e < 8; ++e) VT[(size_t)(vc + e) * MTOK + rot_t(vc + e, row)] = (bf16)((e & 1) ? (wv[e >> 1] >> 16) : (wv[e >> 1] & 0xffffu)); }
.LBB0_430:
	v_lshl_add_u32 v152, s6, 8, v139
	v_ashrrev_i32_e32 v153, 31, v152
	v_lshl_add_u64 v[154:155], v[152:153], 2, s[82:83]
	global_load_dword v136, v[154:155], off
	global_load_dword v248, v[154:155], off offset:64
	global_load_dword v249, v[154:155], off offset:128
	global_load_dword v250, v[154:155], off offset:192
	global_load_dword v251, v[154:155], off offset:512
	global_load_dword v252, v[154:155], off offset:576
	global_load_dword v253, v[154:155], off offset:640
	global_load_dword v254, v[154:155], off offset:704
	s_cmp_lt_i32 s4, 2
	v_mad_i64_i32 v[158:159], s[8:9], v152, s87, 0
	s_cselect_b64 s[8:9], -1, 0
	s_cmp_gt_i32 s4, 1
	s_cselect_b64 s[42:43], -1, 0
	s_cmp_gt_u32 s4, 3
	s_cselect_b64 s[44:45], -1, 0
	s_cmp_gt_u32 s4, 5
	s_cselect_b64 s[36:37], -1, 0
	s_lshl_b32 s28, s4, 8
	s_mov_b32 s29, s13
	s_mov_b64 s[6:7], -1
	s_add_i32 s12, s28, 0xfffffa00
	s_add_i32 s21, s28, 0xfffffc00
	v_readfirstlane_b32 s100, v150
	s_lshr_b32 s100, s100, 6
	s_and_b32 s99, s100, 3
	s_lshl_b32 s99, s99, 5
	s_add_i32 s99, s99, s21
	v_lshrrev_b32_e32 v229, 4, v148
	v_and_b32_e32 v226, 3, v148
	v_lshl_add_u32 v229, v229, 3, v226
	v_add_u32_e32 v229, s99, v229
	v_lshlrev_b32_e32 v232, 16, v229
	v_add_u32_e32 v235, 0x800000, v232
	v_and_b32_e32 v231, 0xff, v229
	v_lshlrev_b32_e32 v231, 7, v231
	v_xor_b32_e32 v234, 0x4000, v231
	v_bfe_u32 v230, v148, 2, 2
	v_lshlrev_b32_e32 v230, 2, v230
	v_and_b32_e32 v226, -16, v152
	v_add_u32_e32 v230, v226, v230
	v_and_b32_e32 v226, 1, v148
	v_cmp_eq_u32_e32 vcc, 1, v226
	v_mov_b32_e32 v233, 0x5040100
	v_mov_b32_e32 v226, 0x3020706
	v_cndmask_b32_e32 v233, v233, v226, vcc
	s_mov_b32 s100, 0xcccccccc
	s_mov_b32 s101, 0xcccccccc
	s_nop 0
	s_nop 0
	s_nop 0
	s_nop 0
	s_nop 0
	s_nop 0
	s_waitcnt vmcnt(0)
	v_fmamk_f32 v136, v136, 0x3a800000, v165
	v_mul_f32_e32 v156, 0x4b800000, v136
	v_cmp_gt_f32_e32 vcc, s85, v136
	s_nop 1
	v_cndmask_b32_e32 v136, v136, v156, vcc
	v_rsq_f32_e32 v136, v136
	v_lshlrev_b64 v[156:157], 10, v[152:153]
	v_mul_f32_e32 v153, 0x45800000, v136
	v_cndmask_b32_e32 v136, v136, v153, vcc
	v_mul_f32_e32 v153, 0x3e000000, v136
	v_cndmask_b32_e64 v160, v136, v153, s[8:9]
	v_pk_mul_f32 v[126:127], v[126:127], v[160:161] op_sel_hi:[1,0]
	v_pk_mul_f32 v[124:125], v[124:125], v[160:161] op_sel_hi:[1,0]
	v_pk_mul_f32 v[166:167], v[122:123], v[160:161] op_sel_hi:[1,0]
	v_pk_mul_f32 v[122:123], v[120:121], v[160:161] op_sel_hi:[1,0]
	v_cvt_pk_bf16_f32 v120, v124, v125
	v_cvt_pk_bf16_f32 v121, v126, v127
	v_cvt_pk_bf16_f32 v122, v122, v123
	v_cvt_pk_bf16_f32 v123, v166, v167
	s_and_b64 vcc, exec, s[42:43]
	s_cbranch_vccz .LBB0_440
	s_mov_b64 s[4:5], -1
	s_and_b64 vcc, exec, s[44:45]
	s_cbranch_vccz .LBB0_437
	s_and_b64 vcc, exec, s[36:37]
	s_cbranch_vccz .LBB0_434
	v_lshl_add_u64 v[124:125], s[80:81], 0, v[158:159]
	v_lshl_add_u64 v[124:125], s[12:13], 1, v[124:125]
	v_lshlrev_b32_e32 v136, 1, v138
	v_lshl_add_u64 v[124:125], v[124:125], 0, v[136:137]
	global_store_dwordx4 v[124:125], v[120:123], off
	s_mov_b64 s[4:5], 0
.LBB0_434:
	s_andn2_b64 vcc, exec, s[4:5]
	s_cbranch_vccnz .LBB0_436
	v_mov_b32_dpp v245, v120 quad_perm:[1,0,3,2] row_mask:0xf bank_mask:0xf
	v_perm_b32 v120, v245, v120, v233
	v_mov_b32_dpp v245, v121 quad_perm:[1,0,3,2] row_mask:0xf bank_mask:0xf
	v_perm_b32 v121, v245, v121, v233
	v_mov_b32_dpp v245, v122 quad_perm:[1,0,3,2] row_mask:0xf bank_mask:0xf
	v_perm_b32 v122, v245, v122, v233
	v_mov_b32_dpp v245, v123 quad_perm:[1,0,3,2] row_mask:0xf bank_mask:0xf
	v_perm_b32 v123, v245, v123, v233
	v_add_u32_e32 v226, v230, v231
	v_add_u32_e32 v227, 0x200, v226
	v_mov_b32_dpp v240, v120 quad_perm:[2,3,0,1] row_mask:0xf bank_mask:0xf
	v_mov_b32_dpp v241, v121 quad_perm:[2,3,0,1] row_mask:0xf bank_mask:0xf
	v_mov_b32_dpp v242, v122 quad_perm:[2,3,0,1] row_mask:0xf bank_mask:0xf
	v_mov_b32_dpp v243, v123 quad_perm:[2,3,0,1] row_mask:0xf bank_mask:0xf
	v_and_b32_e32 v226, 0x7fff, v226
	v_and_b32_e32 v227, 0x7fff, v227
	v_lshl_add_u32 v226, v226, 1, v232
	v_lshl_add_u32 v227, v227, 1, v232
	v_add_u32_e32 v227, 0x40000, v227
	v_cndmask_b32_e64 v236, v120, v241, s[100:101]
	v_cndmask_b32_e64 v237, v240, v121, s[100:101]
	v_cndmask_b32_e64 v238, v122, v243, s[100:101]
	v_cndmask_b32_e64 v239, v242, v123, s[100:101]
	global_store_dwordx2 v226, v[236:237], s[54:55]
	global_store_dwordx2 v227, v[238:239], s[54:55]

; DI unsigned pk2(float lo, float hi) { f32x2_t v = {lo, hi}; bf16x2_t b = __builtin_convertvector(v, bf16x2_t); return __builtin_bit_cast(unsigned, b); }
; DI int rot_t(int c, int t) { return (t + 128 * c) & (MTOK - 1); }
;     DI void operator()(AccRef acc, const Unit& u, int wr, int wc, int fr, int fq) const {
;     ...
;                 for (int bj = 0; bj < 2; ++bj) {
;                     const f32x4 v0 = acc[ai][bj][m][0] * rs, v1 = acc[ai][bj][m][1] * rs;
;                     u32x4 w; w.x = pk2(v0[0], v0[1]); w.y = pk2(v0[2], v0[3]); w.z = pk2(v1[0], v1[1]); w.w = pk2(v1[2], v1[3]);
;                     const int ct = bj * HALF + cb;
;                     if (pn < 2)      *(u32x4*)(Q + (size_t)row * 512 + pn * 256 + ct) = w;
;                     else if (pn < 4) *(u32x4*)(K + (size_t)row * 512 + (pn - 2) * 256 + ct) = w;
;                     else if (pn < 6) { const int vc = (pn - 4) * 256 + ct; const unsigned wv[4] = {w.x, w.y, w.z, w.w};
; _Pragma("unroll")
;                         for (int e = 0; e < 8; ++e) VT[(size_t)(vc + e) * MTOK + rot_t(vc + e, row)] = (bf16)((e & 1) ? (wv[e >> 1] >> 16) : (wv[e >> 1] & 0xffffu)); }
.LBB0_446:
	s_andn2_b64 vcc, exec, s[42:43]
	s_cbranch_vccnz .LBB0_448
	v_mov_b32_dpp v245, v112 quad_perm:[1,0,3,2] row_mask:0xf bank_mask:0xf
	v_perm_b32 v112, v245, v112, v233
	v_mov_b32_dpp v245, v113 quad_perm:[1,0,3,2] row_mask:0xf bank_mask:0xf
	v_perm_b32 v113, v245, v113, v233
	v_mov_b32_dpp v245, v114 quad_perm:[1,0,3,2] row_mask:0xf bank_mask:0xf
	v_perm_b32 v114, v245, v114, v233
	v_mov_b32_dpp v245, v115 quad_perm:[1,0,3,2] row_mask:0xf bank_mask:0xf
	v_perm_b32 v115, v245, v115, v233
	v_add_u32_e32 v226, v230, v234
	v_add_u32_e32 v227, 0x200, v226
	v_mov_b32_dpp v240, v112 quad_perm:[2,3,0,1] row_mask:0xf bank_mask:0xf
	v_mov_b32_dpp v241, v113 quad_perm:[2,3,0,1] row_mask:0xf bank_mask:0xf
	v_mov_b32_dpp v242, v114 quad_perm:[2,3,0,1] row_mask:0xf bank_mask:0xf
	v_mov_b32_dpp v243, v115 quad_perm:[2,3,0,1] row_mask:0xf bank_mask:0xf
	v_and_b32_e32 v226, 0x7fff, v226
	v_and_b32_e32 v227, 0x7fff, v227
	v_lshl_add_u32 v226, v226, 1, v235
	v_lshl_add_u32 v227, v227, 1, v235
	v_add_u32_e32 v227, 0x40000, v227
	v_cndmask_b32_e64 v236, v112, v241, s[100:101]
	v_cndmask_b32_e64 v237, v240, v113, s[100:101]
	v_cndmask_b32_e64 v238, v114, v243, s[100:101]
	v_cndmask_b32_e64 v239, v242, v115, s[100:101]
	global_store_dwordx2 v226, v[236:237], s[54:55]
	global_store_dwordx2 v227, v[238:239], s[54:55]

; DI unsigned pk2(float lo, float hi) { f32x2_t v = {lo, hi}; bf16x2_t b = __builtin_convertvector(v, bf16x2_t); return __builtin_bit_cast(unsigned, b); }
; DI int rot_t(int c, int t) { return (t + 128 * c) & (MTOK - 1); }
;     DI void operator()(AccRef acc, const Unit& u, int wr, int wc, int fr, int fq) const {
;     ...
;                 for (int bj = 0; bj < 2; ++bj) {
;                     const f32x4 v0 = acc[ai][bj][m][0] * rs, v1 = acc[ai][bj][m][1] * rs;
;                     u32x4 w; w.x = pk2(v0[0], v0[1]); w.y = pk2(v0[2], v0[3]); w.z = pk2(v1[0], v1[1]); w.w = pk2(v1[2], v1[3]);
;                     const int ct = bj * HALF + cb;
;                     if (pn < 2)      *(u32x4*)(Q + (size_t)row * 512 + pn * 256 + ct) = w;
;                     else if (pn < 4) *(u32x4*)(K + (size_t)row * 512 + (pn - 2) * 256 + ct) = w;
;                     else if (pn < 6) { const int vc = (pn - 4) * 256 + ct; const unsigned wv[4] = {w.x, w.y, w.z, w.w};
; _Pragma("unroll")
;                         for (int e = 0; e < 8; ++e) VT[(size_t)(vc + e) * MTOK + rot_t(vc + e, row)] = (bf16)((e & 1) ? (wv[e >> 1] >> 16) : (wv[e >> 1] & 0xffffu)); }
.LBB0_458:
	s_andn2_b64 vcc, exec, s[42:43]
	s_cbranch_vccnz .LBB0_460
	v_mov_b32_dpp v245, v104 quad_perm:[1,0,3,2] row_mask:0xf bank_mask:0xf
	v_perm_b32 v104, v245, v104, v233
	v_mov_b32_dpp v245, v105 quad_perm:[1,0,3,2] row_mask:0xf bank_mask:0xf
	v_perm_b32 v105, v245, v105, v233
	v_mov_b32_dpp v245, v106 quad_perm:[1,0,3,2] row_mask:0xf bank_mask:0xf
	v_perm_b32 v106, v245, v106, v233
	v_mov_b32_dpp v245, v107 quad_perm:[1,0,3,2] row_mask:0xf bank_mask:0xf
	v_perm_b32 v107, v245, v107, v233
	v_add_u32_e32 v226, 16, v230
	v_add_u32_e32 v226, v226, v231
	v_add_u32_e32 v227, 0x200, v226
	v_mov_b32_dpp v240, v104 quad_perm:[2,3,0,1] row_mask:0xf bank_mask:0xf
	v_mov_b32_dpp v241, v105 quad_perm:[2,3,0,1] row_mask:0xf bank_mask:0xf
	v_mov_b32_dpp v242, v106 quad_perm:[2,3,0,1] row_mask:0xf bank_mask:0xf
	v_mov_b32_dpp v243, v107 quad_perm:[2,3,0,1] row_mask:0xf bank_mask:0xf
	v_and_b32_e32 v226, 0x7fff, v226
	v_and_b32_e32 v227, 0x7fff, v227
	v_lshl_add_u32 v226, v226, 1, v232
	v_lshl_add_u32 v227, v227, 1, v232
	v_add_u32_e32 v227, 0x40000, v227
	v_cndmask_b32_e64 v236, v104, v241, s[100:101]
	v_cndmask_b32_e64 v237, v240, v105, s[100:101]
	v_cndmask_b32_e64 v238, v106, v243, s[100:101]
	v_cndmask_b32_e64 v239, v242, v107, s[100:101]
	global_store_dwordx2 v226, v[236:237], s[54:55]
	global_store_dwordx2 v227, v[238:239], s[54:55]

; DI unsigned pk2(float lo, float hi) { f32x2_t v = {lo, hi}; bf16x2_t b = __builtin_convertvector(v, bf16x2_t); return __builtin_bit_cast(unsigned, b); }
; DI int rot_t(int c, int t) { return (t + 128 * c) & (MTOK - 1); }
;     DI void operator()(AccRef acc, const Unit& u, int wr, int wc, int fr, int fq) const {
;     ...
;                 for (int bj = 0; bj < 2; ++bj) {
;                     const f32x4 v0 = acc[ai][bj][m][0] * rs, v1 = acc[ai][bj][m][1] * rs;
;                     u32x4 w; w.x = pk2(v0[0], v0[1]); w.y = pk2(v0[2], v0[3]); w.z = pk2(v1[0], v1[1]); w.w = pk2(v1[2], v1[3]);
;                     const int ct = bj * HALF + cb;
;                     if (pn < 2)      *(u32x4*)(Q + (size_t)row * 512 + pn * 256 + ct) = w;
;                     else if (pn < 4) *(u32x4*)(K + (size_t)row * 512 + (pn - 2) * 256 + ct) = w;
;                     else if (pn < 6) { const int vc = (pn - 4) * 256 + ct; const unsigned wv[4] = {w.x, w.y, w.z, w.w};
; _Pragma("unroll")
;                         for (int e = 0; e < 8; ++e) VT[(size_t)(vc + e) * MTOK + rot_t(vc + e, row)] = (bf16)((e & 1) ? (wv[e >> 1] >> 16) : (wv[e >> 1] & 0xffffu)); }
.LBB0_470:
	s_andn2_b64 vcc, exec, s[42:43]
	s_cbranch_vccnz .LBB0_472
	v_mov_b32_dpp v245, v96 quad_perm:[1,0,3,2] row_mask:0xf bank_mask:0xf
	v_perm_b32 v96, v245, v96, v233
	v_mov_b32_dpp v245, v97 quad_perm:[1,0,3,2] row_mask:0xf bank_mask:0xf
	v_perm_b32 v97, v245, v97, v233
	v_mov_b32_dpp v245, v98 quad_perm:[1,0,3,2] row_mask:0xf bank_mask:0xf
	v_perm_b32 v98, v245, v98, v233
	v_mov_b32_dpp v245, v99 quad_perm:[1,0,3,2] row_mask:0xf bank_mask:0xf
	v_perm_b32 v99, v245, v99, v233
	v_add_u32_e32 v226, 16, v230
	v_add_u32_e32 v226, v226, v234
	v_add_u32_e32 v227, 0x200, v226
	v_mov_b32_dpp v240, v96 quad_perm:[2,3,0,1] row_mask:0xf bank_mask:0xf
	v_mov_b32_dpp v241, v97 quad_perm:[2,3,0,1] row_mask:0xf bank_mask:0xf
	v_mov_b32_dpp v242, v98 quad_perm:[2,3,0,1] row_mask:0xf bank_mask:0xf
	v_mov_b32_dpp v243, v99 quad_perm:[2,3,0,1] row_mask:0xf bank_mask:0xf
	v_and_b32_e32 v226, 0x7fff, v226
	v_and_b32_e32 v227, 0x7fff, v227
	v_lshl_add_u32 v226, v226, 1, v235
	v_lshl_add_u32 v227, v227, 1, v235
	v_add_u32_e32 v227, 0x40000, v227
	v_cndmask_b32_e64 v236, v96, v241, s[100:101]
	v_cndmask_b32_e64 v237, v240, v97, s[100:101]
	v_cndmask_b32_e64 v238, v98, v243, s[100:101]
	v_cndmask_b32_e64 v239, v242, v99, s[100:101]
	global_store_dwordx2 v226, v[236:237], s[54:55]
	global_store_dwordx2 v227, v[238:239], s[54:55]

; DI unsigned pk2(float lo, float hi) { f32x2_t v = {lo, hi}; bf16x2_t b = __builtin_convertvector(v, bf16x2_t); return __builtin_bit_cast(unsigned, b); }
; DI int rot_t(int c, int t) { return (t + 128 * c) & (MTOK - 1); }
;     DI void operator()(AccRef acc, const Unit& u, int wr, int wc, int fr, int fq) const {
;     ...
;                 for (int bj = 0; bj < 2; ++bj) {
;                     const f32x4 v0 = acc[ai][bj][m][0] * rs, v1 = acc[ai][bj][m][1] * rs;
;                     u32x4 w; w.x = pk2(v0[0], v0[1]); w.y = pk2(v0[2], v0[3]); w.z = pk2(v1[0], v1[1]); w.w = pk2(v1[2], v1[3]);
;                     const int ct = bj * HALF + cb;
;                     if (pn < 2)      *(u32x4*)(Q + (size_t)row * 512 + pn * 256 + ct) = w;
;                     else if (pn < 4) *(u32x4*)(K + (size_t)row * 512 + (pn - 2) * 256 + ct) = w;
;                     else if (pn < 6) { const int vc = (pn - 4) * 256 + ct; const unsigned wv[4] = {w.x, w.y, w.z, w.w};
; _Pragma("unroll")
;                         for (int e = 0; e < 8; ++e) VT[(size_t)(vc + e) * MTOK + rot_t(vc + e, row)] = (bf16)((e & 1) ? (wv[e >> 1] >> 16) : (wv[e >> 1] & 0xffffu)); }
.LBB0_482:
	s_andn2_b64 vcc, exec, s[42:43]
	s_cbranch_vccnz .LBB0_484
	v_mov_b32_dpp v245, v88 quad_perm:[1,0,3,2] row_mask:0xf bank_mask:0xf
	v_perm_b32 v88, v245, v88, v233
	v_mov_b32_dpp v245, v89 quad_perm:[1,0,3,2] row_mask:0xf bank_mask:0xf
	v_perm_b32 v89, v245, v89, v233
	v_mov_b32_dpp v245, v90 quad_perm:[1,0,3,2] row_mask:0xf bank_mask:0xf
	v_perm_b32 v90, v245, v90, v233
	v_mov_b32_dpp v245, v91 quad_perm:[1,0,3,2] row_mask:0xf bank_mask:0xf
	v_perm_b32 v91, v245, v91, v233
	v_add_u32_e32 v226, 32, v230
	v_add_u32_e32 v226, v226, v231
	v_add_u32_e32 v227, 0x200, v226
	v_mov_b32_dpp v240, v88 quad_perm:[2,3,0,1] row_mask:0xf bank_mask:0xf
	v_mov_b32_dpp v241, v89 quad_perm:[2,3,0,1] row_mask:0xf bank_mask:0xf
	v_mov_b32_dpp v242, v90 quad_perm:[2,3,0,1] row_mask:0xf bank_mask:0xf
	v_mov_b32_dpp v243, v91 quad_perm:[2,3,0,1] row_mask:0xf bank_mask:0xf
	v_and_b32_e32 v226, 0x7fff, v226
	v_and_b32_e32 v227, 0x7fff, v227
	v_lshl_add_u32 v226, v226, 1, v232
	v_lshl_add_u32 v227, v227, 1, v232
	v_add_u32_e32 v227, 0x40000, v227
	v_cndmask_b32_e64 v236, v88, v241, s[100:101]
	v_cndmask_b32_e64 v237, v240, v89, s[100:101]
	v_cndmask_b32_e64 v238, v90, v243, s[100:101]
	v_cndmask_b32_e64 v239, v242, v91, s[100:101]
	global_store_dwordx2 v226, v[236:237], s[54:55]
	global_store_dwordx2 v227, v[238:239], s[54:55]

; DI unsigned pk2(float lo, float hi) { f32x2_t v = {lo, hi}; bf16x2_t b = __builtin_convertvector(v, bf16x2_t); return __builtin_bit_cast(unsigned, b); }
; DI int rot_t(int c, int t) { return (t + 128 * c) & (MTOK - 1); }
;     DI void operator()(AccRef acc, const Unit& u, int wr, int wc, int fr, int fq) const {
;     ...
;                 for (int bj = 0; bj < 2; ++bj) {
;                     const f32x4 v0 = acc[ai][bj][m][0] * rs, v1 = acc[ai][bj][m][1] * rs;
;                     u32x4 w; w.x = pk2(v0[0], v0[1]); w.y = pk2(v0[2], v0[3]); w.z = pk2(v1[0], v1[1]); w.w = pk2(v1[2], v1[3]);
;                     const int ct = bj * HALF + cb;
;                     if (pn < 2)      *(u32x4*)(Q + (size_t)row * 512 + pn * 256 + ct) = w;
;                     else if (pn < 4) *(u32x4*)(K + (size_t)row * 512 + (pn - 2) * 256 + ct) = w;
;                     else if (pn < 6) { const int vc = (pn - 4) * 256 + ct; const unsigned wv[4] = {w.x, w.y, w.z, w.w};
; _Pragma("unroll")
;                         for (int e = 0; e < 8; ++e) VT[(size_t)(vc + e) * MTOK + rot_t(vc + e, row)] = (bf16)((e & 1) ? (wv[e >> 1] >> 16) : (wv[e >> 1] & 0xffffu)); }
.LBB0_494:
	s_andn2_b64 vcc, exec, s[42:43]
	s_cbranch_vccnz .LBB0_496
	v_mov_b32_dpp v245, v80 quad_perm:[1,0,3,2] row_mask:0xf bank_mask:0xf
	v_perm_b32 v80, v245, v80, v233
	v_mov_b32_dpp v245, v81 quad_perm:[1,0,3,2] row_mask:0xf bank_mask:0xf
	v_perm_b32 v81, v245, v81, v233
	v_mov_b32_dpp v245, v82 quad_perm:[1,0,3,2] row_mask:0xf bank_mask:0xf
	v_perm_b32 v82, v245, v82, v233
	v_mov_b32_dpp v245, v83 quad_perm:[1,0,3,2] row_mask:0xf bank_mask:0xf
	v_perm_b32 v83, v245, v83, v233
	v_add_u32_e32 v226, 32, v230
	v_add_u32_e32 v226, v226, v234
	v_add_u32_e32 v227, 0x200, v226
	v_mov_b32_dpp v240, v80 quad_perm:[2,3,0,1] row_mask:0xf bank_mask:0xf
	v_mov_b32_dpp v241, v81 quad_perm:[2,3,0,1] row_mask:0xf bank_mask:0xf
	v_mov_b32_dpp v242, v82 quad_perm:[2,3,0,1] row_mask:0xf bank_mask:0xf
	v_mov_b32_dpp v243, v83 quad_perm:[2,3,0,1] row_mask:0xf bank_mask:0xf
	v_and_b32_e32 v226, 0x7fff, v226
	v_and_b32_e32 v227, 0x7fff, v227
	v_lshl_add_u32 v226, v226, 1, v235
	v_lshl_add_u32 v227, v227, 1, v235
	v_add_u32_e32 v227, 0x40000, v227
	v_cndmask_b32_e64 v236, v80, v241, s[100:101]
	v_cndmask_b32_e64 v237, v240, v81, s[100:101]
	v_cndmask_b32_e64 v238, v82, v243, s[100:101]
	v_cndmask_b32_e64 v239, v242, v83, s[100:101]
	global_store_dwordx2 v226, v[236:237], s[54:55]
	global_store_dwordx2 v227, v[238:239], s[54:55]

; DI unsigned pk2(float lo, float hi) { f32x2_t v = {lo, hi}; bf16x2_t b = __builtin_convertvector(v, bf16x2_t); return __builtin_bit_cast(unsigned, b); }
; DI int rot_t(int c, int t) { return (t + 128 * c) & (MTOK - 1); }
;     DI void operator()(AccRef acc, const Unit& u, int wr, int wc, int fr, int fq) const {
;     ...
;                 for (int bj = 0; bj < 2; ++bj) {
;                     const f32x4 v0 = acc[ai][bj][m][0] * rs, v1 = acc[ai][bj][m][1] * rs;
;                     u32x4 w; w.x = pk2(v0[0], v0[1]); w.y = pk2(v0[2], v0[3]); w.z = pk2(v1[0], v1[1]); w.w = pk2(v1[2], v1[3]);
;                     const int ct = bj * HALF + cb;
;                     if (pn < 2)      *(u32x4*)(Q + (size_t)row * 512 + pn * 256 + ct) = w;
;                     else if (pn < 4) *(u32x4*)(K + (size_t)row * 512 + (pn - 2) * 256 + ct) = w;
;                     else if (pn < 6) { const int vc = (pn - 4) * 256 + ct; const unsigned wv[4] = {w.x, w.y, w.z, w.w};
; _Pragma("unroll")
;                         for (int e = 0; e < 8; ++e) VT[(size_t)(vc + e) * MTOK + rot_t(vc + e, row)] = (bf16)((e & 1) ? (wv[e >> 1] >> 16) : (wv[e >> 1] & 0xffffu)); }
.LBB0_506:
	s_andn2_b64 vcc, exec, s[42:43]
	s_cbranch_vccnz .LBB0_508
	v_mov_b32_dpp v245, v72 quad_perm:[1,0,3,2] row_mask:0xf bank_mask:0xf
	v_perm_b32 v72, v245, v72, v233
	v_mov_b32_dpp v245, v73 quad_perm:[1,0,3,2] row_mask:0xf bank_mask:0xf
	v_perm_b32 v73, v245, v73, v233
	v_mov_b32_dpp v245, v74 quad_perm:[1,0,3,2] row_mask:0xf bank_mask:0xf
	v_perm_b32 v74, v245, v74, v233
	v_mov_b32_dpp v245, v75 quad_perm:[1,0,3,2] row_mask:0xf bank_mask:0xf
	v_perm_b32 v75, v245, v75, v233
	v_add_u32_e32 v226, 48, v230
	v_add_u32_e32 v226, v226, v231
	v_add_u32_e32 v227, 0x200, v226
	v_mov_b32_dpp v240, v72 quad_perm:[2,3,0,1] row_mask:0xf bank_mask:0xf
	v_mov_b32_dpp v241, v73 quad_perm:[2,3,0,1] row_mask:0xf bank_mask:0xf
	v_mov_b32_dpp v242, v74 quad_perm:[2,3,0,1] row_mask:0xf bank_mask:0xf
	v_mov_b32_dpp v243, v75 quad_perm:[2,3,0,1] row_mask:0xf bank_mask:0xf
	v_and_b32_e32 v226, 0x7fff, v226
	v_and_b32_e32 v227, 0x7fff, v227
	v_lshl_add_u32 v226, v226, 1, v232
	v_lshl_add_u32 v227, v227, 1, v232
	v_add_u32_e32 v227, 0x40000, v227
	v_cndmask_b32_e64 v236, v72, v241, s[100:101]
	v_cndmask_b32_e64 v237, v240, v73, s[100:101]
	v_cndmask_b32_e64 v238, v74, v243, s[100:101]
	v_cndmask_b32_e64 v239, v242, v75, s[100:101]
	global_store_dwordx2 v226, v[236:237], s[54:55]
	global_store_dwordx2 v227, v[238:239], s[54:55]

; DI unsigned pk2(float lo, float hi) { f32x2_t v = {lo, hi}; bf16x2_t b = __builtin_convertvector(v, bf16x2_t); return __builtin_bit_cast(unsigned, b); }
; DI int rot_t(int c, int t) { return (t + 128 * c) & (MTOK - 1); }
;     DI void operator()(AccRef acc, const Unit& u, int wr, int wc, int fr, int fq) const {
;     ...
;                 for (int bj = 0; bj < 2; ++bj) {
;                     const f32x4 v0 = acc[ai][bj][m][0] * rs, v1 = acc[ai][bj][m][1] * rs;
;                     u32x4 w; w.x = pk2(v0[0], v0[1]); w.y = pk2(v0[2], v0[3]); w.z = pk2(v1[0], v1[1]); w.w = pk2(v1[2], v1[3]);
;                     const int ct = bj * HALF + cb;
;                     if (pn < 2)      *(u32x4*)(Q + (size_t)row * 512 + pn * 256 + ct) = w;
;                     else if (pn < 4) *(u32x4*)(K + (size_t)row * 512 + (pn - 2) * 256 + ct) = w;
;                     else if (pn < 6) { const int vc = (pn - 4) * 256 + ct; const unsigned wv[4] = {w.x, w.y, w.z, w.w};
; _Pragma("unroll")
;                         for (int e = 0; e < 8; ++e) VT[(size_t)(vc + e) * MTOK + rot_t(vc + e, row)] = (bf16)((e & 1) ? (wv[e >> 1] >> 16) : (wv[e >> 1] & 0xffffu)); }
.LBB0_518:
	s_andn2_b64 vcc, exec, s[42:43]
	s_cbranch_vccnz .LBB0_520
	v_mov_b32_dpp v245, v64 quad_perm:[1,0,3,2] row_mask:0xf bank_mask:0xf
	v_perm_b32 v64, v245, v64, v233
	v_mov_b32_dpp v245, v65 quad_perm:[1,0,3,2] row_mask:0xf bank_mask:0xf
	v_perm_b32 v65, v245, v65, v233
	v_mov_b32_dpp v245, v66 quad_perm:[1,0,3,2] row_mask:0xf bank_mask:0xf
	v_perm_b32 v66, v245, v66, v233
	v_mov_b32_dpp v245, v67 quad_perm:[1,0,3,2] row_mask:0xf bank_mask:0xf
	v_perm_b32 v67, v245, v67, v233
	v_add_u32_e32 v226, 48, v230
	v_add_u32_e32 v226, v226, v234
	v_add_u32_e32 v227, 0x200, v226
	v_mov_b32_dpp v240, v64 quad_perm:[2,3,0,1] row_mask:0xf bank_mask:0xf
	v_mov_b32_dpp v241, v65 quad_perm:[2,3,0,1] row_mask:0xf bank_mask:0xf
	v_mov_b32_dpp v242, v66 quad_perm:[2,3,0,1] row_mask:0xf bank_mask:0xf
	v_mov_b32_dpp v243, v67 quad_perm:[2,3,0,1] row_mask:0xf bank_mask:0xf
	v_and_b32_e32 v226, 0x7fff, v226
	v_and_b32_e32 v227, 0x7fff, v227
	v_lshl_add_u32 v226, v226, 1, v235
	v_lshl_add_u32 v227, v227, 1, v235
	v_add_u32_e32 v227, 0x40000, v227
	v_cndmask_b32_e64 v236, v64, v241, s[100:101]
	v_cndmask_b32_e64 v237, v240, v65, s[100:101]
	v_cndmask_b32_e64 v238, v66, v243, s[100:101]
	v_cndmask_b32_e64 v239, v242, v67, s[100:101]
	global_store_dwordx2 v226, v[236:237], s[54:55]
	global_store_dwordx2 v227, v[238:239], s[54:55]

; DI unsigned pk2(float lo, float hi) { f32x2_t v = {lo, hi}; bf16x2_t b = __builtin_convertvector(v, bf16x2_t); return __builtin_bit_cast(unsigned, b); }
; DI int rot_t(int c, int t) { return (t + 128 * c) & (MTOK - 1); }
;     DI void operator()(AccRef acc, const Unit& u, int wr, int wc, int fr, int fq) const {
;     ...
;                 for (int bj = 0; bj < 2; ++bj) {
;                     const f32x4 v0 = acc[ai][bj][m][0] * rs, v1 = acc[ai][bj][m][1] * rs;
;                     u32x4 w; w.x = pk2(v0[0], v0[1]); w.y = pk2(v0[2], v0[3]); w.z = pk2(v1[0], v1[1]); w.w = pk2(v1[2], v1[3]);
;                     const int ct = bj * HALF + cb;
;                     if (pn < 2)      *(u32x4*)(Q + (size_t)row * 512 + pn * 256 + ct) = w;
;                     else if (pn < 4) *(u32x4*)(K + (size_t)row * 512 + (pn - 2) * 256 + ct) = w;
;                     else if (pn < 6) { const int vc = (pn - 4) * 256 + ct; const unsigned wv[4] = {w.x, w.y, w.z, w.w};
; _Pragma("unroll")
;                         for (int e = 0; e < 8; ++e) VT[(size_t)(vc + e) * MTOK + rot_t(vc + e, row)] = (bf16)((e & 1) ? (wv[e >> 1] >> 16) : (wv[e >> 1] & 0xffffu)); }
.LBB0_530:
	s_andn2_b64 vcc, exec, s[42:43]
	s_cbranch_vccnz .LBB0_532
	v_mov_b32_dpp v245, v56 quad_perm:[1,0,3,2] row_mask:0xf bank_mask:0xf
	v_perm_b32 v56, v245, v56, v233
	v_mov_b32_dpp v245, v57 quad_perm:[1,0,3,2] row_mask:0xf bank_mask:0xf
	v_perm_b32 v57, v245, v57, v233
	v_mov_b32_dpp v245, v58 quad_perm:[1,0,3,2] row_mask:0xf bank_mask:0xf
	v_perm_b32 v58, v245, v58, v233
	v_mov_b32_dpp v245, v59 quad_perm:[1,0,3,2] row_mask:0xf bank_mask:0xf
	v_perm_b32 v59, v245, v59, v233
	v_add_u32_e32 v226, 128, v230
	v_add_u32_e32 v226, v226, v231
	v_add_u32_e32 v227, 0x200, v226
	v_mov_b32_dpp v240, v56 quad_perm:[2,3,0,1] row_mask:0xf bank_mask:0xf
	v_mov_b32_dpp v241, v57 quad_perm:[2,3,0,1] row_mask:0xf bank_mask:0xf
	v_mov_b32_dpp v242, v58 quad_perm:[2,3,0,1] row_mask:0xf bank_mask:0xf
	v_mov_b32_dpp v243, v59 quad_perm:[2,3,0,1] row_mask:0xf bank_mask:0xf
	v_and_b32_e32 v226, 0x7fff, v226
	v_and_b32_e32 v227, 0x7fff, v227
	v_lshl_add_u32 v226, v226, 1, v232
	v_lshl_add_u32 v227, v227, 1, v232
	v_add_u32_e32 v227, 0x40000, v227
	v_cndmask_b32_e64 v236, v56, v241, s[100:101]
	v_cndmask_b32_e64 v237, v240, v57, s[100:101]
	v_cndmask_b32_e64 v238, v58, v243, s[100:101]
	v_cndmask_b32_e64 v239, v242, v59, s[100:101]
	global_store_dwordx2 v226, v[236:237], s[54:55]
	global_store_dwordx2 v227, v[238:239], s[54:55]

; DI unsigned pk2(float lo, float hi) { f32x2_t v = {lo, hi}; bf16x2_t b = __builtin_convertvector(v, bf16x2_t); return __builtin_bit_cast(unsigned, b); }
; DI int rot_t(int c, int t) { return (t + 128 * c) & (MTOK - 1); }
;     DI void operator()(AccRef acc, const Unit& u, int wr, int wc, int fr, int fq) const {
;     ...
;                 for (int bj = 0; bj < 2; ++bj) {
;                     const f32x4 v0 = acc[ai][bj][m][0] * rs, v1 = acc[ai][bj][m][1] * rs;
;                     u32x4 w; w.x = pk2(v0[0], v0[1]); w.y = pk2(v0[2], v0[3]); w.z = pk2(v1[0], v1[1]); w.w = pk2(v1[2], v1[3]);
;                     const int ct = bj * HALF + cb;
;                     if (pn < 2)      *(u32x4*)(Q + (size_t)row * 512 + pn * 256 + ct) = w;
;                     else if (pn < 4) *(u32x4*)(K + (size_t)row * 512 + (pn - 2) * 256 + ct) = w;
;                     else if (pn < 6) { const int vc = (pn - 4) * 256 + ct; const unsigned wv[4] = {w.x, w.y, w.z, w.w};
; _Pragma("unroll")
;                         for (int e = 0; e < 8; ++e) VT[(size_t)(vc + e) * MTOK + rot_t(vc + e, row)] = (bf16)((e & 1) ? (wv[e >> 1] >> 16) : (wv[e >> 1] & 0xffffu)); }
.LBB0_542:
	s_andn2_b64 vcc, exec, s[42:43]
	s_cbranch_vccnz .LBB0_544
	v_mov_b32_dpp v245, v48 quad_perm:[1,0,3,2] row_mask:0xf bank_mask:0xf
	v_perm_b32 v48, v245, v48, v233
	v_mov_b32_dpp v245, v49 quad_perm:[1,0,3,2] row_mask:0xf bank_mask:0xf
	v_perm_b32 v49, v245, v49, v233
	v_mov_b32_dpp v245, v50 quad_perm:[1,0,3,2] row_mask:0xf bank_mask:0xf
	v_perm_b32 v50, v245, v50, v233
	v_mov_b32_dpp v245, v51 quad_perm:[1,0,3,2] row_mask:0xf bank_mask:0xf
	v_perm_b32 v51, v245, v51, v233
	v_add_u32_e32 v226, 128, v230
	v_add_u32_e32 v226, v226, v234
	v_add_u32_e32 v227, 0x200, v226
	v_mov_b32_dpp v240, v48 quad_perm:[2,3,0,1] row_mask:0xf bank_mask:0xf
	v_mov_b32_dpp v241, v49 quad_perm:[2,3,0,1] row_mask:0xf bank_mask:0xf
	v_mov_b32_dpp v242, v50 quad_perm:[2,3,0,1] row_mask:0xf bank_mask:0xf
	v_mov_b32_dpp v243, v51 quad_perm:[2,3,0,1] row_mask:0xf bank_mask:0xf
	v_and_b32_e32 v226, 0x7fff, v226
	v_and_b32_e32 v227, 0x7fff, v227
	v_lshl_add_u32 v226, v226, 1, v235
	v_lshl_add_u32 v227, v227, 1, v235
	v_add_u32_e32 v227, 0x40000, v227
	v_cndmask_b32_e64 v236, v48, v241, s[100:101]
	v_cndmask_b32_e64 v237, v240, v49, s[100:101]
	v_cndmask_b32_e64 v238, v50, v243, s[100:101]
	v_cndmask_b32_e64 v239, v242, v51, s[100:101]
	global_store_dwordx2 v226, v[236:237], s[54:55]
	global_store_dwordx2 v227, v[238:239], s[54:55]

; DI unsigned pk2(float lo, float hi) { f32x2_t v = {lo, hi}; bf16x2_t b = __builtin_convertvector(v, bf16x2_t); return __builtin_bit_cast(unsigned, b); }
; DI int rot_t(int c, int t) { return (t + 128 * c) & (MTOK - 1); }
;     DI void operator()(AccRef acc, const Unit& u, int wr, int wc, int fr, int fq) const {
;     ...
;                 for (int bj = 0; bj < 2; ++bj) {
;                     const f32x4 v0 = acc[ai][bj][m][0] * rs, v1 = acc[ai][bj][m][1] * rs;
;                     u32x4 w; w.x = pk2(v0[0], v0[1]); w.y = pk2(v0[2], v0[3]); w.z = pk2(v1[0], v1[1]); w.w = pk2(v1[2], v1[3]);
;                     const int ct = bj * HALF + cb;
;                     if (pn < 2)      *(u32x4*)(Q + (size_t)row * 512 + pn * 256 + ct) = w;
;                     else if (pn < 4) *(u32x4*)(K + (size_t)row * 512 + (pn - 2) * 256 + ct) = w;
;                     else if (pn < 6) { const int vc = (pn - 4) * 256 + ct; const unsigned wv[4] = {w.x, w.y, w.z, w.w};
; _Pragma("unroll")
;                         for (int e = 0; e < 8; ++e) VT[(size_t)(vc + e) * MTOK + rot_t(vc + e, row)] = (bf16)((e & 1) ? (wv[e >> 1] >> 16) : (wv[e >> 1] & 0xffffu)); }
.LBB0_554:
	s_andn2_b64 vcc, exec, s[42:43]
	s_cbranch_vccnz .LBB0_556
	v_mov_b32_dpp v245, v40 quad_perm:[1,0,3,2] row_mask:0xf bank_mask:0xf
	v_perm_b32 v40, v245, v40, v233
	v_mov_b32_dpp v245, v41 quad_perm:[1,0,3,2] row_mask:0xf bank_mask:0xf
	v_perm_b32 v41, v245, v41, v233
	v_mov_b32_dpp v245, v42 quad_perm:[1,0,3,2] row_mask:0xf bank_mask:0xf
	v_perm_b32 v42, v245, v42, v233
	v_mov_b32_dpp v245, v43 quad_perm:[1,0,3,2] row_mask:0xf bank_mask:0xf
	v_perm_b32 v43, v245, v43, v233
	v_add_u32_e32 v226, 144, v230
	v_add_u32_e32 v226, v226, v231
	v_add_u32_e32 v227, 0x200, v226
	v_mov_b32_dpp v240, v40 quad_perm:[2,3,0,1] row_mask:0xf bank_mask:0xf
	v_mov_b32_dpp v241, v41 quad_perm:[2,3,0,1] row_mask:0xf bank_mask:0xf
	v_mov_b32_dpp v242, v42 quad_perm:[2,3,0,1] row_mask:0xf bank_mask:0xf
	v_mov_b32_dpp v243, v43 quad_perm:[2,3,0,1] row_mask:0xf bank_mask:0xf
	v_and_b32_e32 v226, 0x7fff, v226
	v_and_b32_e32 v227, 0x7fff, v227
	v_lshl_add_u32 v226, v226, 1, v232
	v_lshl_add_u32 v227, v227, 1, v232
	v_add_u32_e32 v227, 0x40000, v227
	v_cndmask_b32_e64 v236, v40, v241, s[100:101]
	v_cndmask_b32_e64 v237, v240, v41, s[100:101]
	v_cndmask_b32_e64 v238, v42, v243, s[100:101]
	v_cndmask_b32_e64 v239, v242, v43, s[100:101]
	global_store_dwordx2 v226, v[236:237], s[54:55]
	global_store_dwordx2 v227, v[238:239], s[54:55]

; DI unsigned pk2(float lo, float hi) { f32x2_t v = {lo, hi}; bf16x2_t b = __builtin_convertvector(v, bf16x2_t); return __builtin_bit_cast(unsigned, b); }
; DI int rot_t(int c, int t) { return (t + 128 * c) & (MTOK - 1); }
;     DI void operator()(AccRef acc, const Unit& u, int wr, int wc, int fr, int fq) const {
;     ...
;                 for (int bj = 0; bj < 2; ++bj) {
;                     const f32x4 v0 = acc[ai][bj][m][0] * rs, v1 = acc[ai][bj][m][1] * rs;
;                     u32x4 w; w.x = pk2(v0[0], v0[1]); w.y = pk2(v0[2], v0[3]); w.z = pk2(v1[0], v1[1]); w.w = pk2(v1[2], v1[3]);
;                     const int ct = bj * HALF + cb;
;                     if (pn < 2)      *(u32x4*)(Q + (size_t)row * 512 + pn * 256 + ct) = w;
;                     else if (pn < 4) *(u32x4*)(K + (size_t)row * 512 + (pn - 2) * 256 + ct) = w;
;                     else if (pn < 6) { const int vc = (pn - 4) * 256 + ct; const unsigned wv[4] = {w.x, w.y, w.z, w.w};
; _Pragma("unroll")
;                         for (int e = 0; e < 8; ++e) VT[(size_t)(vc + e) * MTOK + rot_t(vc + e, row)] = (bf16)((e & 1) ? (wv[e >> 1] >> 16) : (wv[e >> 1] & 0xffffu)); }
.LBB0_566:
	s_andn2_b64 vcc, exec, s[42:43]
	s_cbranch_vccnz .LBB0_568
	v_mov_b32_dpp v245, v32 quad_perm:[1,0,3,2] row_mask:0xf bank_mask:0xf
	v_perm_b32 v32, v245, v32, v233
	v_mov_b32_dpp v245, v33 quad_perm:[1,0,3,2] row_mask:0xf bank_mask:0xf
	v_perm_b32 v33, v245, v33, v233
	v_mov_b32_dpp v245, v34 quad_perm:[1,0,3,2] row_mask:0xf bank_mask:0xf
	v_perm_b32 v34, v245, v34, v233
	v_mov_b32_dpp v245, v35 quad_perm:[1,0,3,2] row_mask:0xf bank_mask:0xf
	v_perm_b32 v35, v245, v35, v233
	v_add_u32_e32 v226, 144, v230
	v_add_u32_e32 v226, v226, v234
	v_add_u32_e32 v227, 0x200, v226
	v_mov_b32_dpp v240, v32 quad_perm:[2,3,0,1] row_mask:0xf bank_mask:0xf
	v_mov_b32_dpp v241, v33 quad_perm:[2,3,0,1] row_mask:0xf bank_mask:0xf
	v_mov_b32_dpp v242, v34 quad_perm:[2,3,0,1] row_mask:0xf bank_mask:0xf
	v_mov_b32_dpp v243, v35 quad_perm:[2,3,0,1] row_mask:0xf bank_mask:0xf
	v_and_b32_e32 v226, 0x7fff, v226
	v_and_b32_e32 v227, 0x7fff, v227
	v_lshl_add_u32 v226, v226, 1, v235
	v_lshl_add_u32 v227, v227, 1, v235
	v_add_u32_e32 v227, 0x40000, v227
	v_cndmask_b32_e64 v236, v32, v241, s[100:101]
	v_cndmask_b32_e64 v237, v240, v33, s[100:101]
	v_cndmask_b32_e64 v238, v34, v243, s[100:101]
	v_cndmask_b32_e64 v239, v242, v35, s[100:101]
	global_store_dwordx2 v226, v[236:237], s[54:55]
	global_store_dwordx2 v227, v[238:239], s[54:55]

; DI unsigned pk2(float lo, float hi) { f32x2_t v = {lo, hi}; bf16x2_t b = __builtin_convertvector(v, bf16x2_t); return __builtin_bit_cast(unsigned, b); }
; DI int rot_t(int c, int t) { return (t + 128 * c) & (MTOK - 1); }
;     DI void operator()(AccRef acc, const Unit& u, int wr, int wc, int fr, int fq) const {
;     ...
;                 for (int bj = 0; bj < 2; ++bj) {
;                     const f32x4 v0 = acc[ai][bj][m][0] * rs, v1 = acc[ai][bj][m][1] * rs;
;                     u32x4 w; w.x = pk2(v0[0], v0[1]); w.y = pk2(v0[2], v0[3]); w.z = pk2(v1[0], v1[1]); w.w = pk2(v1[2], v1[3]);
;                     const int ct = bj * HALF + cb;
;                     if (pn < 2)      *(u32x4*)(Q + (size_t)row * 512 + pn * 256 + ct) = w;
;                     else if (pn < 4) *(u32x4*)(K + (size_t)row * 512 + (pn - 2) * 256 + ct) = w;
;                     else if (pn < 6) { const int vc = (pn - 4) * 256 + ct; const unsigned wv[4] = {w.x, w.y, w.z, w.w};
; _Pragma("unroll")
;                         for (int e = 0; e < 8; ++e) VT[(size_t)(vc + e) * MTOK + rot_t(vc + e, row)] = (bf16)((e & 1) ? (wv[e >> 1] >> 16) : (wv[e >> 1] & 0xffffu)); }
.LBB0_578:
	s_andn2_b64 vcc, exec, s[42:43]
	s_cbranch_vccnz .LBB0_580
	v_mov_b32_dpp v245, v24 quad_perm:[1,0,3,2] row_mask:0xf bank_mask:0xf
	v_perm_b32 v24, v245, v24, v233
	v_mov_b32_dpp v245, v25 quad_perm:[1,0,3,2] row_mask:0xf bank_mask:0xf
	v_perm_b32 v25, v245, v25, v233
	v_mov_b32_dpp v245, v26 quad_perm:[1,0,3,2] row_mask:0xf bank_mask:0xf
	v_perm_b32 v26, v245, v26, v233
	v_mov_b32_dpp v245, v27 quad_perm:[1,0,3,2] row_mask:0xf bank_mask:0xf
	v_perm_b32 v27, v245, v27, v233
	v_add_u32_e32 v226, 160, v230
	v_add_u32_e32 v226, v226, v231
	v_add_u32_e32 v227, 0x200, v226
	v_mov_b32_dpp v240, v24 quad_perm:[2,3,0,1] row_mask:0xf bank_mask:0xf
	v_mov_b32_dpp v241, v25 quad_perm:[2,3,0,1] row_mask:0xf bank_mask:0xf
	v_mov_b32_dpp v242, v26 quad_perm:[2,3,0,1] row_mask:0xf bank_mask:0xf
	v_mov_b32_dpp v243, v27 quad_perm:[2,3,0,1] row_mask:0xf bank_mask:0xf
	v_and_b32_e32 v226, 0x7fff, v226
	v_and_b32_e32 v227, 0x7fff, v227
	v_lshl_add_u32 v226, v226, 1, v232
	v_lshl_add_u32 v227, v227, 1, v232
	v_add_u32_e32 v227, 0x40000, v227
	v_cndmask_b32_e64 v236, v24, v241, s[100:101]
	v_cndmask_b32_e64 v237, v240, v25, s[100:101]
	v_cndmask_b32_e64 v238, v26, v243, s[100:101]
	v_cndmask_b32_e64 v239, v242, v27, s[100:101]
	global_store_dwordx2 v226, v[236:237], s[54:55]
	global_store_dwordx2 v227, v[238:239], s[54:55]

; DI unsigned pk2(float lo, float hi) { f32x2_t v = {lo, hi}; bf16x2_t b = __builtin_convertvector(v, bf16x2_t); return __builtin_bit_cast(unsigned, b); }
; DI int rot_t(int c, int t) { return (t + 128 * c) & (MTOK - 1); }
;     DI void operator()(AccRef acc, const Unit& u, int wr, int wc, int fr, int fq) const {
;     ...
;                 for (int bj = 0; bj < 2; ++bj) {
;                     const f32x4 v0 = acc[ai][bj][m][0] * rs, v1 = acc[ai][bj][m][1] * rs;
;                     u32x4 w; w.x = pk2(v0[0], v0[1]); w.y = pk2(v0[2], v0[3]); w.z = pk2(v1[0], v1[1]); w.w = pk2(v1[2], v1[3]);
;                     const int ct = bj * HALF + cb;
;                     if (pn < 2)      *(u32x4*)(Q + (size_t)row * 512 + pn * 256 + ct) = w;
;                     else if (pn < 4) *(u32x4*)(K + (size_t)row * 512 + (pn - 2) * 256 + ct) = w;
;                     else if (pn < 6) { const int vc = (pn - 4) * 256 + ct; const unsigned wv[4] = {w.x, w.y, w.z, w.w};
; _Pragma("unroll")
;                         for (int e = 0; e < 8; ++e) VT[(size_t)(vc + e) * MTOK + rot_t(vc + e, row)] = (bf16)((e & 1) ? (wv[e >> 1] >> 16) : (wv[e >> 1] & 0xffffu)); }
.LBB0_590:
	s_andn2_b64 vcc, exec, s[42:43]
	s_cbranch_vccnz .LBB0_592
	v_mov_b32_dpp v245, v16 quad_perm:[1,0,3,2] row_mask:0xf bank_mask:0xf
	v_perm_b32 v16, v245, v16, v233
	v_mov_b32_dpp v245, v17 quad_perm:[1,0,3,2] row_mask:0xf bank_mask:0xf
	v_perm_b32 v17, v245, v17, v233
	v_mov_b32_dpp v245, v18 quad_perm:[1,0,3,2] row_mask:0xf bank_mask:0xf
	v_perm_b32 v18, v245, v18, v233
	v_mov_b32_dpp v245, v19 quad_perm:[1,0,3,2] row_mask:0xf bank_mask:0xf
	v_perm_b32 v19, v245, v19, v233
	v_add_u32_e32 v226, 160, v230
	v_add_u32_e32 v226, v226, v234
	v_add_u32_e32 v227, 0x200, v226
	v_mov_b32_dpp v240, v16 quad_perm:[2,3,0,1] row_mask:0xf bank_mask:0xf
	v_mov_b32_dpp v241, v17 quad_perm:[2,3,0,1] row_mask:0xf bank_mask:0xf
	v_mov_b32_dpp v242, v18 quad_perm:[2,3,0,1] row_mask:0xf bank_mask:0xf
	v_mov_b32_dpp v243, v19 quad_perm:[2,3,0,1] row_mask:0xf bank_mask:0xf
	v_and_b32_e32 v226, 0x7fff, v226
	v_and_b32_e32 v227, 0x7fff, v227
	v_lshl_add_u32 v226, v226, 1, v235
	v_lshl_add_u32 v227, v227, 1, v235
	v_add_u32_e32 v227, 0x40000, v227
	v_cndmask_b32_e64 v236, v16, v241, s[100:101]
	v_cndmask_b32_e64 v237, v240, v17, s[100:101]
	v_cndmask_b32_e64 v238, v18, v243, s[100:101]
	v_cndmask_b32_e64 v239, v242, v19, s[100:101]
	global_store_dwordx2 v226, v[236:237], s[54:55]
	global_store_dwordx2 v227, v[238:239], s[54:55]

; DI unsigned pk2(float lo, float hi) { f32x2_t v = {lo, hi}; bf16x2_t b = __builtin_convertvector(v, bf16x2_t); return __builtin_bit_cast(unsigned, b); }
; DI int rot_t(int c, int t) { return (t + 128 * c) & (MTOK - 1); }
;     DI void operator()(AccRef acc, const Unit& u, int wr, int wc, int fr, int fq) const {
;     ...
;                 for (int bj = 0; bj < 2; ++bj) {
;                     const f32x4 v0 = acc[ai][bj][m][0] * rs, v1 = acc[ai][bj][m][1] * rs;
;                     u32x4 w; w.x = pk2(v0[0], v0[1]); w.y = pk2(v0[2], v0[3]); w.z = pk2(v1[0], v1[1]); w.w = pk2(v1[2], v1[3]);
;                     const int ct = bj * HALF + cb;
;                     if (pn < 2)      *(u32x4*)(Q + (size_t)row * 512 + pn * 256 + ct) = w;
;                     else if (pn < 4) *(u32x4*)(K + (size_t)row * 512 + (pn - 2) * 256 + ct) = w;
;                     else if (pn < 6) { const int vc = (pn - 4) * 256 + ct; const unsigned wv[4] = {w.x, w.y, w.z, w.w};
; _Pragma("unroll")
;                         for (int e = 0; e < 8; ++e) VT[(size_t)(vc + e) * MTOK + rot_t(vc + e, row)] = (bf16)((e & 1) ? (wv[e >> 1] >> 16) : (wv[e >> 1] & 0xffffu)); }
.LBB0_602:
	s_andn2_b64 vcc, exec, s[8:9]
	s_cbranch_vccnz .LBB0_604
	v_mov_b32_dpp v245, v8 quad_perm:[1,0,3,2] row_mask:0xf bank_mask:0xf
	v_perm_b32 v8, v245, v8, v233
	v_mov_b32_dpp v245, v9 quad_perm:[1,0,3,2] row_mask:0xf bank_mask:0xf
	v_perm_b32 v9, v245, v9, v233
	v_mov_b32_dpp v245, v10 quad_perm:[1,0,3,2] row_mask:0xf bank_mask:0xf
	v_perm_b32 v10, v245, v10, v233
	v_mov_b32_dpp v245, v11 quad_perm:[1,0,3,2] row_mask:0xf bank_mask:0xf
	v_perm_b32 v11, v245, v11, v233
	v_add_u32_e32 v226, 176, v230
	v_add_u32_e32 v226, v226, v231
	v_add_u32_e32 v227, 0x200, v226
	v_mov_b32_dpp v240, v8 quad_perm:[2,3,0,1] row_mask:0xf bank_mask:0xf
	v_mov_b32_dpp v241, v9 quad_perm:[2,3,0,1] row_mask:0xf bank_mask:0xf
	v_mov_b32_dpp v242, v10 quad_perm:[2,3,0,1] row_mask:0xf bank_mask:0xf
	v_mov_b32_dpp v243, v11 quad_perm:[2,3,0,1] row_mask:0xf bank_mask:0xf
	v_and_b32_e32 v226, 0x7fff, v226
	v_and_b32_e32 v227, 0x7fff, v227
	v_lshl_add_u32 v226, v226, 1, v232
	v_lshl_add_u32 v227, v227, 1, v232
	v_add_u32_e32 v227, 0x40000, v227
	v_cndmask_b32_e64 v236, v8, v241, s[100:101]
	v_cndmask_b32_e64 v237, v240, v9, s[100:101]
	v_cndmask_b32_e64 v238, v10, v243, s[100:101]
	v_cndmask_b32_e64 v239, v242, v11, s[100:101]
	global_store_dwordx2 v226, v[236:237], s[54:55]
	global_store_dwordx2 v227, v[238:239], s[54:55]

; DI unsigned pk2(float lo, float hi) { f32x2_t v = {lo, hi}; bf16x2_t b = __builtin_convertvector(v, bf16x2_t); return __builtin_bit_cast(unsigned, b); }
; DI int rot_t(int c, int t) { return (t + 128 * c) & (MTOK - 1); }
;     DI void operator()(AccRef acc, const Unit& u, int wr, int wc, int fr, int fq) const {
;     ...
;                 for (int bj = 0; bj < 2; ++bj) {
;                     const f32x4 v0 = acc[ai][bj][m][0] * rs, v1 = acc[ai][bj][m][1] * rs;
;                     u32x4 w; w.x = pk2(v0[0], v0[1]); w.y = pk2(v0[2], v0[3]); w.z = pk2(v1[0], v1[1]); w.w = pk2(v1[2], v1[3]);
;                     const int ct = bj * HALF + cb;
;                     if (pn < 2)      *(u32x4*)(Q + (size_t)row * 512 + pn * 256 + ct) = w;
;                     else if (pn < 4) *(u32x4*)(K + (size_t)row * 512 + (pn - 2) * 256 + ct) = w;
;                     else if (pn < 6) { const int vc = (pn - 4) * 256 + ct; const unsigned wv[4] = {w.x, w.y, w.z, w.w};
; _Pragma("unroll")
;                         for (int e = 0; e < 8; ++e) VT[(size_t)(vc + e) * MTOK + rot_t(vc + e, row)] = (bf16)((e & 1) ? (wv[e >> 1] >> 16) : (wv[e >> 1] & 0xffffu)); }
.LBB0_616:
	s_andn2_b64 vcc, exec, s[4:5]
	s_cbranch_vccnz .LBB0_618
	v_mov_b32_dpp v245, v0 quad_perm:[1,0,3,2] row_mask:0xf bank_mask:0xf
	v_perm_b32 v0, v245, v0, v233
	v_mov_b32_dpp v245, v1 quad_perm:[1,0,3,2] row_mask:0xf bank_mask:0xf
	v_perm_b32 v1, v245, v1, v233
	v_mov_b32_dpp v245, v2 quad_perm:[1,0,3,2] row_mask:0xf bank_mask:0xf
	v_perm_b32 v2, v245, v2, v233
	v_mov_b32_dpp v245, v3 quad_perm:[1,0,3,2] row_mask:0xf bank_mask:0xf
	v_perm_b32 v3, v245, v3, v233
	v_add_u32_e32 v226, 176, v230
	v_add_u32_e32 v226, v226, v234
	v_add_u32_e32 v227, 0x200, v226
	v_mov_b32_dpp v240, v0 quad_perm:[2,3,0,1] row_mask:0xf bank_mask:0xf
	v_mov_b32_dpp v241, v1 quad_perm:[2,3,0,1] row_mask:0xf bank_mask:0xf
	v_mov_b32_dpp v242, v2 quad_perm:[2,3,0,1] row_mask:0xf bank_mask:0xf
	v_mov_b32_dpp v243, v3 quad_perm:[2,3,0,1] row_mask:0xf bank_mask:0xf
	v_and_b32_e32 v226, 0x7fff, v226
	v_and_b32_e32 v227, 0x7fff, v227
	v_lshl_add_u32 v226, v226, 1, v235
	v_lshl_add_u32 v227, v227, 1, v235
	v_add_u32_e32 v227, 0x40000, v227
	v_cndmask_b32_e64 v236, v0, v241, s[100:101]
	v_cndmask_b32_e64 v237, v240, v1, s[100:101]
	v_cndmask_b32_e64 v238, v2, v243, s[100:101]
	v_cndmask_b32_e64 v239, v242, v3, s[100:101]
	global_store_dwordx2 v226, v[236:237], s[54:55]
	global_store_dwordx2 v227, v[238:239], s[54:55]
